# diff attention step A: per-iteration v_cndmask + v_cmp_ne recompute of the negated loop-invariant mask replaced by one s_andn2_b64
# speedup vs baseline: 1.0013x; 1.0009x over previous
.LBB0_494:
	s_lshl_b32 s6, s6, 1
	v_add_u32_e32 v231, s6, v252
	ds_read_b64_tr_b16 v[196:197], v231 offset:24576
	ds_read_b64_tr_b16 v[198:199], v231 offset:25088
	s_waitcnt lgkmcnt(9)
	v_mfma_f32_32x32x16_bf16 v[116:131], v[192:195], v[160:163], 0
	v_add_f32_e32 v100, v84, v85
	v_add_f32_e32 v100, v86, v100
	v_add_f32_e32 v100, v87, v100
	v_add_f32_e32 v100, v88, v100
	v_add_f32_e32 v132, v89, v100
	v_cvt_pk_bf16_f32 v144, v84, v85
	v_cvt_pk_bf16_f32 v145, v86, v87
	ds_read_b64_tr_b16 v[84:85], v231 offset:28672
	ds_read_b64_tr_b16 v[86:87], v231 offset:29184
	s_waitcnt lgkmcnt(10)
	v_mfma_f32_32x32x16_bf16 v[100:115], v[188:191], v[160:163], 0
	v_add_f32_e32 v132, v90, v132
	v_add_f32_e32 v132, v91, v132
	v_add_f32_e32 v132, v92, v132
	v_add_f32_e32 v132, v93, v132
	v_cvt_pk_bf16_f32 v146, v88, v89
	v_cvt_pk_bf16_f32 v147, v90, v91
	ds_read_b64_tr_b16 v[88:89], v231 offset:32768
	ds_read_b64_tr_b16 v[90:91], v231 offset:33280
	s_waitcnt lgkmcnt(11)
	v_mfma_f32_32x32x16_bf16 v[116:131], v[184:187], v[156:159], v[116:131]
	v_add_f32_e32 v132, v94, v132
	v_add_f32_e32 v132, v95, v132
	v_add_f32_e32 v132, v96, v132
	v_add_f32_e32 v132, v97, v132
	v_cvt_pk_bf16_f32 v140, v92, v93
	v_cvt_pk_bf16_f32 v141, v94, v95
	ds_read_b64_tr_b16 v[92:93], v231 offset:36864
	ds_read_b64_tr_b16 v[94:95], v231 offset:37376
	s_waitcnt lgkmcnt(12)
	v_mfma_f32_32x32x16_bf16 v[100:115], v[180:183], v[156:159], v[100:115]
	v_add_f32_e32 v132, v98, v132
	v_add_f32_e32 v132, v99, v132
	v_add_f32_e32 v132, v68, v132
	v_add_f32_e32 v132, v69, v132
	v_cvt_pk_bf16_f32 v142, v96, v97
	v_cvt_pk_bf16_f32 v143, v98, v99
	ds_read_b64_tr_b16 v[96:97], v231 offset:25600
	ds_read_b64_tr_b16 v[98:99], v231 offset:26112
	s_waitcnt lgkmcnt(13)
	v_mfma_f32_32x32x16_bf16 v[116:131], v[176:179], v[152:155], v[116:131]
	v_add_f32_e32 v132, v70, v132
	v_add_f32_e32 v132, v71, v132
	v_add_f32_e32 v132, v72, v132
	v_add_f32_e32 v132, v73, v132
	v_cvt_pk_bf16_f32 v136, v68, v69
	v_cvt_pk_bf16_f32 v137, v70, v71
	ds_read_b64_tr_b16 v[68:69], v231 offset:29696
	ds_read_b64_tr_b16 v[70:71], v231 offset:30208
	s_waitcnt lgkmcnt(14)
	v_mfma_f32_32x32x16_bf16 v[100:115], v[172:175], v[152:155], v[100:115]
	v_add_f32_e32 v132, v74, v132
	v_add_f32_e32 v132, v75, v132
	v_add_f32_e32 v132, v76, v132
	v_add_f32_e32 v132, v77, v132
	v_cvt_pk_bf16_f32 v138, v72, v73
	v_cvt_pk_bf16_f32 v139, v74, v75
	ds_read_b64_tr_b16 v[72:73], v231 offset:33792
	ds_read_b64_tr_b16 v[74:75], v231 offset:34304
	s_waitcnt lgkmcnt(14)
	v_mfma_f32_32x32x16_bf16 v[116:131], v[168:171], v[148:151], v[116:131]
	v_add_f32_e32 v132, v78, v132
	v_add_f32_e32 v132, v79, v132
	v_add_f32_e32 v132, v80, v132
	v_add_f32_e32 v168, v81, v132
	v_cvt_pk_bf16_f32 v132, v76, v77
	v_cvt_pk_bf16_f32 v133, v78, v79
	ds_read_b64_tr_b16 v[76:77], v231 offset:37888
	ds_read_b64_tr_b16 v[78:79], v231 offset:38400
	v_mfma_f32_32x32x16_bf16 v[100:115], v[164:167], v[148:151], v[100:115]
	v_add_f32_e32 v134, v82, v168
	v_add_f32_e32 v134, v83, v134
	v_add_f32_e32 v164, 0, v134
	v_cvt_pk_bf16_f32 v134, v80, v81
	v_cvt_pk_bf16_f32 v135, v82, v83
	v_add_f32_e32 v192, v229, v164
	s_andn2_b64 s[10:11], exec, s[4:5]
	s_andn2_b64 vcc, exec, s[4:5]
	s_mov_b64 s[6:7], 0
	s_cbranch_vccz .LBB0_502
